# v112 + P3 weight-transpose stores written through (sc1)
# baseline (speedup 1.0000x reference)
.LBB0_501:
	global_load_dword v4, v[2:3], off nt
	v_lshl_add_u64 v[2:3], v[2:3], 0, s[6:7]
	global_load_dword v5, v[2:3], off nt
	v_lshl_add_u64 v[2:3], v[2:3], 0, s[6:7]
	global_load_dword v6, v[2:3], off nt
	v_lshl_add_u64 v[2:3], v[2:3], 0, s[6:7]
	global_load_dword v7, v[2:3], off nt
	v_lshl_add_u64 v[2:3], v[2:3], 0, s[6:7]
	global_load_dword v8, v[2:3], off nt
	v_lshl_add_u64 v[2:3], v[2:3], 0, s[6:7]
	global_load_dword v9, v[2:3], off nt
	v_lshl_add_u64 v[2:3], v[2:3], 0, s[6:7]
	global_load_dword v10, v[2:3], off nt
	v_lshl_add_u64 v[2:3], v[2:3], 0, s[6:7]
	global_load_dword v15, v[2:3], off nt
	v_lshl_add_u64 v[2:3], v[2:3], 0, s[6:7]
	global_load_dword v17, v[2:3], off nt
	v_lshl_add_u64 v[2:3], v[2:3], 0, s[6:7]
	global_load_dword v18, v[2:3], off nt
	v_lshl_add_u64 v[2:3], v[2:3], 0, s[6:7]
	global_load_dword v19, v[2:3], off nt
	v_lshl_add_u64 v[2:3], v[2:3], 0, s[6:7]
	global_load_dword v20, v[2:3], off nt
	v_lshl_add_u64 v[2:3], v[2:3], 0, s[6:7]
	global_load_dword v21, v[2:3], off nt
	v_lshl_add_u64 v[2:3], v[2:3], 0, s[6:7]
	global_load_dword v22, v[2:3], off nt
	v_lshl_add_u64 v[2:3], v[2:3], 0, s[6:7]
	global_load_dword v23, v[2:3], off nt
	v_lshl_add_u64 v[2:3], v[2:3], 0, s[6:7]
	global_load_dword v53, v[2:3], off nt
	v_or_b32_e32 v54, s10, v24
	s_movk_i32 s10, 0x104
	v_mad_u32_u24 v54, v54, s10, v25
	v_lshl_add_u64 v[2:3], v[2:3], 0, s[6:7]
	s_movk_i32 s10, 0x80
	s_and_b64 vcc, exec, s[8:9]
	s_mov_b64 s[8:9], 0
	s_waitcnt vmcnt(15)
	ds_write_b32 v54, v4
	s_waitcnt vmcnt(14)
	ds_write_b32 v54, v5 offset:2080
	s_waitcnt vmcnt(13)
	ds_write_b32 v54, v6 offset:4160
	s_waitcnt vmcnt(12)
	ds_write_b32 v54, v7 offset:6240
	s_waitcnt vmcnt(11)
	ds_write_b32 v54, v8 offset:8320
	s_waitcnt vmcnt(10)
	ds_write_b32 v54, v9 offset:10400
	s_waitcnt vmcnt(9)
	ds_write_b32 v54, v10 offset:12480
	s_waitcnt vmcnt(8)
	ds_write_b32 v54, v15 offset:14560
	s_waitcnt vmcnt(7)
	ds_write_b32 v54, v17 offset:16640
	s_waitcnt vmcnt(6)
	ds_write_b32 v54, v18 offset:18720
	s_waitcnt vmcnt(5)
	ds_write_b32 v54, v19 offset:20800
	s_waitcnt vmcnt(4)
	ds_write_b32 v54, v20 offset:22880
	s_waitcnt vmcnt(3)
	ds_write_b32 v54, v21 offset:24960
	s_waitcnt vmcnt(2)
	ds_write_b32 v54, v22 offset:27040
	s_waitcnt vmcnt(1)
	ds_write_b32 v54, v23 offset:29120
	s_waitcnt vmcnt(0)
	ds_write_b32 v54, v53 offset:31200
	s_cbranch_vccnz .LBB0_501
	s_waitcnt lgkmcnt(0)
	s_barrier
	ds_read2_b32 v[6:7], v26 offset1:32
	v_add_u32_e32 v2, 0x400, v27
	ds_read2_b32 v[8:9], v2 offset0:4 offset1:36
	ds_read2_b32 v[18:19], v26 offset0:65 offset1:97
	ds_read2_b32 v[20:21], v2 offset0:69 offset1:101
	ds_read2_b32 v[22:23], v26 offset0:130 offset1:162
	ds_read2_b32 v[54:55], v26 offset0:195 offset1:227
	ds_read2_b32 v[56:57], v2 offset0:134 offset1:166
	ds_read2_b32 v[58:59], v2 offset0:199 offset1:231
	s_lshl_b32 s6, s19, 1
	ds_read2_b32 v[64:65], v29 offset1:65
	s_waitcnt lgkmcnt(6)
	v_cvt_pk_bf16_f32 v2, v6, v18
	v_or_b32_e32 v6, s18, v142
	v_mul_u32_u24_e32 v10, s27, v6
	v_add_u32_e32 v6, 0x400, v30
	ds_read2_b32 v[66:67], v29 offset0:130 offset1:195
	ds_read2_b32 v[68:69], v6 offset0:4 offset1:69
	ds_read2_b32 v[70:71], v6 offset0:134 offset1:199
	s_add_u32 s4, s4, s6
	s_addc_u32 s5, s5, 0
	v_mov_b32_e32 v17, v11
	v_lshl_add_u64 v[60:61], s[4:5], 0, v[16:17]
	v_or_b32_e32 v6, s18, v28
	s_waitcnt lgkmcnt(6)
	v_cvt_pk_bf16_f32 v3, v22, v54
	v_cvt_pk_bf16_f32 v4, v8, v20
	s_waitcnt lgkmcnt(4)
	v_cvt_pk_bf16_f32 v5, v56, v58
	v_lshl_add_u64 v[62:63], v[10:11], 1, v[60:61]
	v_mul_u32_u24_e32 v10, s27, v6
	global_store_dwordx4 v[62:63], v[2:5], off sc1
	v_lshl_add_u64 v[62:63], v[10:11], 1, v[60:61]
	v_or_b32_e32 v6, s18, v31
	s_waitcnt lgkmcnt(3)
	v_cvt_pk_bf16_f32 v2, v64, v65
	s_waitcnt lgkmcnt(2)
	v_cvt_pk_bf16_f32 v3, v66, v67
	s_waitcnt lgkmcnt(1)
	v_cvt_pk_bf16_f32 v4, v68, v69
	s_waitcnt lgkmcnt(0)
	v_cvt_pk_bf16_f32 v5, v70, v71
	global_store_dwordx4 v[62:63], v[2:5], off sc1
	v_mul_u32_u24_e32 v10, s27, v6
	s_mov_b64 s[4:5], 0
	v_cvt_pk_bf16_f32 v2, v7, v19
	v_cvt_pk_bf16_f32 v3, v23, v55
	v_cvt_pk_bf16_f32 v4, v9, v21
	v_lshl_add_u64 v[6:7], v[10:11], 1, v[60:61]
	ds_read2_b32 v[8:9], v33 offset1:65
	v_add_u32_e32 v10, 0x400, v34
	ds_read2_b32 v[18:19], v33 offset0:130 offset1:195
	ds_read2_b32 v[20:21], v10 offset0:4 offset1:69
	ds_read2_b32 v[22:23], v10 offset0:134 offset1:199
	v_cvt_pk_bf16_f32 v5, v57, v59
	global_store_dwordx4 v[6:7], v[2:5], off sc1
	v_add_u32_e32 v6, s18, v32
	v_mul_hi_u32_u24_e32 v7, s27, v6
	v_mul_u32_u24_e32 v6, s27, v6
	s_waitcnt lgkmcnt(3)
	v_cvt_pk_bf16_f32 v2, v8, v9
	s_waitcnt lgkmcnt(2)
	v_cvt_pk_bf16_f32 v3, v18, v19
	s_waitcnt lgkmcnt(1)
	v_cvt_pk_bf16_f32 v4, v20, v21
	s_waitcnt lgkmcnt(0)
	v_cvt_pk_bf16_f32 v5, v22, v23
	v_lshl_add_u64 v[6:7], v[6:7], 1, v[60:61]
	global_store_dwordx4 v[6:7], v[2:5], off sc1
	s_barrier

.LBB0_529:
	s_or_b64 exec, exec, s[4:5]
	s_waitcnt lgkmcnt(1)
	v_cvt_pk_bf16_f32 v2, v2, v3
	v_cvt_pk_bf16_f32 v3, v4, v5
	s_waitcnt lgkmcnt(0)
	v_cvt_pk_bf16_f32 v4, v6, v7
	v_lshl_add_u32 v6, v15, 4, s18
	v_cvt_pk_bf16_f32 v5, v8, v9
	v_or_b32_e32 v8, v6, v17
	v_mov_b64_e32 v[6:7], s[34:35]
	s_movk_i32 s4, 0x500
	v_mad_i64_i32 v[6:7], s[4:5], v8, s4, v[6:7]
	v_lshlrev_b32_e32 v10, 1, v10
	s_addk_i32 s19, 0x200
	v_lshl_add_u64 v[6:7], v[6:7], 0, v[10:11]
	s_cmpk_eq_i32 s19, 0x2800
	global_store_dwordx4 v[6:7], v[2:5], off sc1
	s_cbranch_scc1 .LBB0_535

.LBB0_536:
	v_add_u32_e32 v10, s4, v2
	v_add_u32_e32 v4, s4, v3
	v_and_b32_e32 v6, 63, v10
	s_movk_i32 s5, 0x108
	v_ashrrev_i32_e32 v5, 31, v4
	v_lshl_add_u32 v17, v6, 7, v38
	v_mad_u32_u24 v15, v6, s5, v37
	v_lshlrev_b64 v[8:9], 10, v[4:5]
	ds_read_b128 v[4:7], v17 offset:512
	ds_read_b128 v[18:21], v17 offset:528
	ds_read_b128 v[54:57], v17 offset:544
	ds_read_b128 v[58:61], v17 offset:560
	ds_read_b64 v[22:23], v15 offset:16896
	s_waitcnt lgkmcnt(4)
	v_mov_b32_e32 v62, v5
	v_mov_b32_e32 v63, v6
	s_waitcnt lgkmcnt(3)
	v_mov_b32_e32 v64, v19
	v_mov_b32_e32 v65, v20
	s_waitcnt lgkmcnt(2)
	v_mov_b32_e32 v66, v55
	v_mov_b32_e32 v67, v56
	s_waitcnt lgkmcnt(1)
	v_mov_b32_e32 v69, v60
	v_mov_b32_e32 v70, v7
	v_mov_b32_e32 v71, v4
	v_mov_b32_e32 v72, v4
	v_mov_b32_e32 v73, v6
	v_mov_b32_e32 v6, v5
	v_mov_b32_e32 v4, v21
	v_mov_b32_e32 v5, v18
	v_mov_b32_e32 v74, v18
	v_mov_b32_e32 v75, v20
	v_mov_b32_e32 v20, v19
	v_mov_b32_e32 v18, v57
	v_mov_b32_e32 v19, v54
	v_mov_b32_e32 v76, v54
	v_mov_b32_e32 v77, v56
	v_mov_b32_e32 v56, v55
	v_mov_b32_e32 v54, v61
	v_mov_b32_e32 v55, v58
	v_mov_b32_e32 v79, v60
	v_mov_b32_e32 v60, v59
	v_mov_b32_e32 v68, v59
	v_mov_b32_e32 v78, v58
	s_waitcnt lgkmcnt(0)
	v_pk_mul_f32 v[58:59], v[22:23], v[70:71]
	v_pk_mul_f32 v[6:7], v[22:23], v[6:7] op_sel:[1,0]
	v_pk_mul_f32 v[4:5], v[22:23], v[4:5]
	v_pk_mul_f32 v[20:21], v[22:23], v[20:21] op_sel:[1,0]
	v_pk_mul_f32 v[18:19], v[22:23], v[18:19]
	v_pk_mul_f32 v[56:57], v[22:23], v[56:57] op_sel:[1,0]
	v_pk_mul_f32 v[54:55], v[22:23], v[54:55]
	v_pk_mul_f32 v[60:61], v[22:23], v[60:61] op_sel:[1,0]
	v_pk_fma_f32 v[58:59], v[22:23], v[62:63], v[58:59] op_sel:[0,0,1] op_sel_hi:[1,1,0]
	v_pk_fma_f32 v[6:7], v[22:23], v[72:73], v[6:7] op_sel_hi:[0,1,1] neg_lo:[0,0,1] neg_hi:[0,0,1]
	v_pk_fma_f32 v[4:5], v[22:23], v[64:65], v[4:5] op_sel:[0,0,1] op_sel_hi:[1,1,0]
	v_pk_fma_f32 v[20:21], v[22:23], v[74:75], v[20:21] op_sel_hi:[0,1,1] neg_lo:[0,0,1] neg_hi:[0,0,1]
	v_pk_fma_f32 v[18:19], v[22:23], v[66:67], v[18:19] op_sel:[0,0,1] op_sel_hi:[1,1,0]
	v_pk_fma_f32 v[56:57], v[22:23], v[76:77], v[56:57] op_sel_hi:[0,1,1] neg_lo:[0,0,1] neg_hi:[0,0,1]
	v_pk_fma_f32 v[54:55], v[22:23], v[68:69], v[54:55] op_sel:[0,0,1] op_sel_hi:[1,1,0]
	v_pk_fma_f32 v[22:23], v[22:23], v[78:79], v[60:61] op_sel_hi:[0,1,1] neg_lo:[0,0,1] neg_hi:[0,0,1]
	v_cmp_lt_u32_e32 vcc, 63, v10
	s_add_i32 s4, s4, 8
	s_cmp_lg_u32 s4, 32
	v_cndmask_b32_e32 v7, v7, v59, vcc
	v_cndmask_b32_e32 v6, v6, v58, vcc
	v_cndmask_b32_e32 v5, v21, v5, vcc
	v_cndmask_b32_e32 v10, v20, v4, vcc
	v_cndmask_b32_e32 v15, v57, v19, vcc
	v_cndmask_b32_e32 v17, v56, v18, vcc
	v_cndmask_b32_e32 v18, v23, v55, vcc
	v_cndmask_b32_e32 v19, v22, v54, vcc
	v_lshl_add_u64 v[8:9], v[12:13], 0, v[8:9]
	v_cvt_pk_bf16_f32 v4, v6, v7
	v_cvt_pk_bf16_f32 v5, v10, v5
	v_cvt_pk_bf16_f32 v6, v17, v15
	v_cvt_pk_bf16_f32 v7, v19, v18
	global_store_dwordx4 v[8:9], v[4:7], off sc1
	s_cbranch_scc1 .LBB0_536
	s_barrier
	s_branch .LBB0_459
